# phase 0 adaLN GEMV: weight-row loads double-buffered (16 rows in flight instead of a drain every 8 rows), counted vmcnt
# baseline (speedup 1.0000x reference)
.LBB0_27:
	s_mov_b64 s[34:35], 0xc000
	v_lshl_add_u64 v[90:91], v[16:17], 0, s[16:17]
	global_load_dwordx4 v[22:25], v[90:91], off nt
	v_lshl_add_u64 v[90:91], v[90:91], 0, s[34:35]
	global_load_dwordx4 v[26:29], v[90:91], off nt
	v_lshl_add_u64 v[90:91], v[90:91], 0, s[34:35]
	global_load_dwordx4 v[30:33], v[90:91], off nt
	v_lshl_add_u64 v[90:91], v[90:91], 0, s[34:35]
	global_load_dwordx4 v[34:37], v[90:91], off nt
	v_lshl_add_u64 v[90:91], v[90:91], 0, s[34:35]
	global_load_dwordx4 v[38:41], v[90:91], off nt
	v_lshl_add_u64 v[90:91], v[90:91], 0, s[34:35]
	global_load_dwordx4 v[42:45], v[90:91], off nt
	v_lshl_add_u64 v[90:91], v[90:91], 0, s[34:35]
	global_load_dwordx4 v[46:49], v[90:91], off nt
	v_lshl_add_u64 v[90:91], v[90:91], 0, s[34:35]
	global_load_dwordx4 v[50:53], v[90:91], off nt
.Lgv_loop:
	s_add_u32 s16, s16, 0x60000
	s_addc_u32 s17, s17, 0
	v_lshl_add_u64 v[90:91], v[16:17], 0, s[16:17]
	global_load_dwordx4 v[100:103], v[90:91], off nt
	v_lshl_add_u64 v[90:91], v[90:91], 0, s[34:35]
	global_load_dwordx4 v[104:107], v[90:91], off nt
	v_lshl_add_u64 v[90:91], v[90:91], 0, s[34:35]
	global_load_dwordx4 v[108:111], v[90:91], off nt
	v_lshl_add_u64 v[90:91], v[90:91], 0, s[34:35]
	global_load_dwordx4 v[112:115], v[90:91], off nt
	v_lshl_add_u64 v[90:91], v[90:91], 0, s[34:35]
	global_load_dwordx4 v[116:119], v[90:91], off nt
	v_lshl_add_u64 v[90:91], v[90:91], 0, s[34:35]
	global_load_dwordx4 v[120:123], v[90:91], off nt
	v_lshl_add_u64 v[90:91], v[90:91], 0, s[34:35]
	global_load_dwordx4 v[124:127], v[90:91], off nt
	v_lshl_add_u64 v[90:91], v[90:91], 0, s[34:35]
	global_load_dwordx4 v[128:131], v[90:91], off nt
	v_mov_b32_e32 v74, s13
	ds_read_b128 v[54:57], v74
	ds_read_b128 v[58:61], v74 offset:16
	ds_read_b128 v[62:65], v74 offset:512
	ds_read_b128 v[66:69], v74 offset:528
	ds_read_b128 v[70:73], v74 offset:1024
	ds_read_b128 v[74:77], v74 offset:1040
	s_waitcnt lgkmcnt(5)
	v_mov_b32_e32 v78, v57
	s_waitcnt lgkmcnt(3)
	v_mov_b32_e32 v80, v65
	v_mov_b32_e32 v84, v61
	s_waitcnt lgkmcnt(1)
	v_mov_b32_e32 v82, v73
	v_mov_b32_e32 v86, v69
	s_waitcnt lgkmcnt(0)
	v_mov_b32_e32 v88, v77
	s_add_i32 s13, s13, 32
	s_waitcnt vmcnt(15)
	v_pk_fma_f32 v[6:7], v[24:25], v[54:55], v[6:7] op_sel_hi:[1,0,1]
	v_pk_fma_f32 v[4:5], v[22:23], v[54:55], v[4:5] op_sel_hi:[1,0,1]
	v_pk_fma_f32 v[10:11], v[24:25], v[62:63], v[10:11] op_sel_hi:[1,0,1]
	v_pk_fma_f32 v[8:9], v[22:23], v[62:63], v[8:9] op_sel_hi:[1,0,1]
	v_pk_fma_f32 v[2:3], v[24:25], v[70:71], v[2:3] op_sel_hi:[1,0,1]
	v_pk_fma_f32 v[0:1], v[22:23], v[70:71], v[0:1] op_sel_hi:[1,0,1]
	s_waitcnt vmcnt(14)
	v_pk_fma_f32 v[4:5], v[26:27], v[54:55], v[4:5] op_sel:[0,1,0]
	v_pk_fma_f32 v[6:7], v[28:29], v[54:55], v[6:7] op_sel:[0,1,0]
	v_pk_fma_f32 v[8:9], v[26:27], v[62:63], v[8:9] op_sel:[0,1,0]
	v_pk_fma_f32 v[10:11], v[28:29], v[62:63], v[10:11] op_sel:[0,1,0]
	v_pk_fma_f32 v[0:1], v[26:27], v[70:71], v[0:1] op_sel:[0,1,0]
	v_pk_fma_f32 v[2:3], v[28:29], v[70:71], v[2:3] op_sel:[0,1,0]
	s_waitcnt vmcnt(13)
	v_pk_fma_f32 v[6:7], v[32:33], v[56:57], v[6:7] op_sel_hi:[1,0,1]
	v_pk_fma_f32 v[4:5], v[30:31], v[56:57], v[4:5] op_sel_hi:[1,0,1]
	v_pk_fma_f32 v[10:11], v[32:33], v[64:65], v[10:11] op_sel_hi:[1,0,1]
	v_pk_fma_f32 v[8:9], v[30:31], v[64:65], v[8:9] op_sel_hi:[1,0,1]
	v_pk_fma_f32 v[2:3], v[32:33], v[72:73], v[2:3] op_sel_hi:[1,0,1]
	v_pk_fma_f32 v[0:1], v[30:31], v[72:73], v[0:1] op_sel_hi:[1,0,1]
	s_waitcnt vmcnt(12)
	v_pk_fma_f32 v[6:7], v[36:37], v[78:79], v[6:7] op_sel_hi:[1,0,1]
	v_pk_fma_f32 v[4:5], v[34:35], v[78:79], v[4:5] op_sel_hi:[1,0,1]
	v_pk_fma_f32 v[10:11], v[36:37], v[80:81], v[10:11] op_sel_hi:[1,0,1]
	v_pk_fma_f32 v[8:9], v[34:35], v[80:81], v[8:9] op_sel_hi:[1,0,1]
	v_pk_fma_f32 v[2:3], v[36:37], v[82:83], v[2:3] op_sel_hi:[1,0,1]
	v_pk_fma_f32 v[0:1], v[34:35], v[82:83], v[0:1] op_sel_hi:[1,0,1]
	s_waitcnt vmcnt(11)
	v_pk_fma_f32 v[6:7], v[40:41], v[58:59], v[6:7] op_sel_hi:[1,0,1]
	v_pk_fma_f32 v[4:5], v[38:39], v[58:59], v[4:5] op_sel_hi:[1,0,1]
	v_pk_fma_f32 v[10:11], v[40:41], v[66:67], v[10:11] op_sel_hi:[1,0,1]
	v_pk_fma_f32 v[8:9], v[38:39], v[66:67], v[8:9] op_sel_hi:[1,0,1]
	v_pk_fma_f32 v[2:3], v[40:41], v[74:75], v[2:3] op_sel_hi:[1,0,1]
	v_pk_fma_f32 v[0:1], v[38:39], v[74:75], v[0:1] op_sel_hi:[1,0,1]
	s_waitcnt vmcnt(10)
	v_pk_fma_f32 v[6:7], v[44:45], v[58:59], v[6:7] op_sel:[0,1,0]
	v_pk_fma_f32 v[4:5], v[42:43], v[58:59], v[4:5] op_sel:[0,1,0]
	v_pk_fma_f32 v[10:11], v[44:45], v[66:67], v[10:11] op_sel:[0,1,0]
	v_pk_fma_f32 v[8:9], v[42:43], v[66:67], v[8:9] op_sel:[0,1,0]
	v_pk_fma_f32 v[2:3], v[44:45], v[74:75], v[2:3] op_sel:[0,1,0]
	v_pk_fma_f32 v[0:1], v[42:43], v[74:75], v[0:1] op_sel:[0,1,0]
	s_waitcnt vmcnt(9)
	v_pk_fma_f32 v[6:7], v[48:49], v[60:61], v[6:7] op_sel_hi:[1,0,1]
	v_pk_fma_f32 v[4:5], v[46:47], v[60:61], v[4:5] op_sel_hi:[1,0,1]
	v_pk_fma_f32 v[10:11], v[48:49], v[68:69], v[10:11] op_sel_hi:[1,0,1]
	v_pk_fma_f32 v[8:9], v[46:47], v[68:69], v[8:9] op_sel_hi:[1,0,1]
	v_pk_fma_f32 v[2:3], v[48:49], v[76:77], v[2:3] op_sel_hi:[1,0,1]
	v_pk_fma_f32 v[0:1], v[46:47], v[76:77], v[0:1] op_sel_hi:[1,0,1]
	s_waitcnt vmcnt(8)
	v_pk_fma_f32 v[6:7], v[52:53], v[84:85], v[6:7] op_sel_hi:[1,0,1]
	v_pk_fma_f32 v[4:5], v[50:51], v[84:85], v[4:5] op_sel_hi:[1,0,1]
	v_pk_fma_f32 v[10:11], v[52:53], v[86:87], v[10:11] op_sel_hi:[1,0,1]
	v_pk_fma_f32 v[8:9], v[50:51], v[86:87], v[8:9] op_sel_hi:[1,0,1]
	v_pk_fma_f32 v[2:3], v[52:53], v[88:89], v[2:3] op_sel_hi:[1,0,1]
	v_pk_fma_f32 v[0:1], v[50:51], v[88:89], v[0:1] op_sel_hi:[1,0,1]
	s_add_u32 s16, s16, 0x60000
	s_addc_u32 s17, s17, 0
	s_cmp_eq_u32 s16, 0x600000
	s_cbranch_scc1 .Lgv_tail
	v_lshl_add_u64 v[90:91], v[16:17], 0, s[16:17]
	global_load_dwordx4 v[22:25], v[90:91], off nt
	v_lshl_add_u64 v[90:91], v[90:91], 0, s[34:35]
	global_load_dwordx4 v[26:29], v[90:91], off nt
	v_lshl_add_u64 v[90:91], v[90:91], 0, s[34:35]
	global_load_dwordx4 v[30:33], v[90:91], off nt
	v_lshl_add_u64 v[90:91], v[90:91], 0, s[34:35]
	global_load_dwordx4 v[34:37], v[90:91], off nt
	v_lshl_add_u64 v[90:91], v[90:91], 0, s[34:35]
	global_load_dwordx4 v[38:41], v[90:91], off nt
	v_lshl_add_u64 v[90:91], v[90:91], 0, s[34:35]
	global_load_dwordx4 v[42:45], v[90:91], off nt
	v_lshl_add_u64 v[90:91], v[90:91], 0, s[34:35]
	global_load_dwordx4 v[46:49], v[90:91], off nt
	v_lshl_add_u64 v[90:91], v[90:91], 0, s[34:35]
	global_load_dwordx4 v[50:53], v[90:91], off nt
	v_mov_b32_e32 v74, s13
	ds_read_b128 v[54:57], v74
	ds_read_b128 v[58:61], v74 offset:16
	ds_read_b128 v[62:65], v74 offset:512
	ds_read_b128 v[66:69], v74 offset:528
	ds_read_b128 v[70:73], v74 offset:1024
	ds_read_b128 v[74:77], v74 offset:1040
	s_waitcnt lgkmcnt(5)
	v_mov_b32_e32 v78, v57
	s_waitcnt lgkmcnt(3)
	v_mov_b32_e32 v80, v65
	v_mov_b32_e32 v84, v61
	s_waitcnt lgkmcnt(1)
	v_mov_b32_e32 v82, v73
	v_mov_b32_e32 v86, v69
	s_waitcnt lgkmcnt(0)
	v_mov_b32_e32 v88, v77
	s_add_i32 s13, s13, 32
	s_waitcnt vmcnt(15)
	v_pk_fma_f32 v[6:7], v[102:103], v[54:55], v[6:7] op_sel_hi:[1,0,1]
	v_pk_fma_f32 v[4:5], v[100:101], v[54:55], v[4:5] op_sel_hi:[1,0,1]
	v_pk_fma_f32 v[10:11], v[102:103], v[62:63], v[10:11] op_sel_hi:[1,0,1]
	v_pk_fma_f32 v[8:9], v[100:101], v[62:63], v[8:9] op_sel_hi:[1,0,1]
	v_pk_fma_f32 v[2:3], v[102:103], v[70:71], v[2:3] op_sel_hi:[1,0,1]
	v_pk_fma_f32 v[0:1], v[100:101], v[70:71], v[0:1] op_sel_hi:[1,0,1]
	s_waitcnt vmcnt(14)
	v_pk_fma_f32 v[4:5], v[104:105], v[54:55], v[4:5] op_sel:[0,1,0]
	v_pk_fma_f32 v[6:7], v[106:107], v[54:55], v[6:7] op_sel:[0,1,0]
	v_pk_fma_f32 v[8:9], v[104:105], v[62:63], v[8:9] op_sel:[0,1,0]
	v_pk_fma_f32 v[10:11], v[106:107], v[62:63], v[10:11] op_sel:[0,1,0]
	v_pk_fma_f32 v[0:1], v[104:105], v[70:71], v[0:1] op_sel:[0,1,0]
	v_pk_fma_f32 v[2:3], v[106:107], v[70:71], v[2:3] op_sel:[0,1,0]
	s_waitcnt vmcnt(13)
	v_pk_fma_f32 v[6:7], v[110:111], v[56:57], v[6:7] op_sel_hi:[1,0,1]
	v_pk_fma_f32 v[4:5], v[108:109], v[56:57], v[4:5] op_sel_hi:[1,0,1]
	v_pk_fma_f32 v[10:11], v[110:111], v[64:65], v[10:11] op_sel_hi:[1,0,1]
	v_pk_fma_f32 v[8:9], v[108:109], v[64:65], v[8:9] op_sel_hi:[1,0,1]
	v_pk_fma_f32 v[2:3], v[110:111], v[72:73], v[2:3] op_sel_hi:[1,0,1]
	v_pk_fma_f32 v[0:1], v[108:109], v[72:73], v[0:1] op_sel_hi:[1,0,1]
	s_waitcnt vmcnt(12)
	v_pk_fma_f32 v[6:7], v[114:115], v[78:79], v[6:7] op_sel_hi:[1,0,1]
	v_pk_fma_f32 v[4:5], v[112:113], v[78:79], v[4:5] op_sel_hi:[1,0,1]
	v_pk_fma_f32 v[10:11], v[114:115], v[80:81], v[10:11] op_sel_hi:[1,0,1]
	v_pk_fma_f32 v[8:9], v[112:113], v[80:81], v[8:9] op_sel_hi:[1,0,1]
	v_pk_fma_f32 v[2:3], v[114:115], v[82:83], v[2:3] op_sel_hi:[1,0,1]
	v_pk_fma_f32 v[0:1], v[112:113], v[82:83], v[0:1] op_sel_hi:[1,0,1]
	s_waitcnt vmcnt(11)
	v_pk_fma_f32 v[6:7], v[118:119], v[58:59], v[6:7] op_sel_hi:[1,0,1]
	v_pk_fma_f32 v[4:5], v[116:117], v[58:59], v[4:5] op_sel_hi:[1,0,1]
	v_pk_fma_f32 v[10:11], v[118:119], v[66:67], v[10:11] op_sel_hi:[1,0,1]
	v_pk_fma_f32 v[8:9], v[116:117], v[66:67], v[8:9] op_sel_hi:[1,0,1]
	v_pk_fma_f32 v[2:3], v[118:119], v[74:75], v[2:3] op_sel_hi:[1,0,1]
	v_pk_fma_f32 v[0:1], v[116:117], v[74:75], v[0:1] op_sel_hi:[1,0,1]
	s_waitcnt vmcnt(10)
	v_pk_fma_f32 v[6:7], v[122:123], v[58:59], v[6:7] op_sel:[0,1,0]
	v_pk_fma_f32 v[4:5], v[120:121], v[58:59], v[4:5] op_sel:[0,1,0]
	v_pk_fma_f32 v[10:11], v[122:123], v[66:67], v[10:11] op_sel:[0,1,0]
	v_pk_fma_f32 v[8:9], v[120:121], v[66:67], v[8:9] op_sel:[0,1,0]
	v_pk_fma_f32 v[2:3], v[122:123], v[74:75], v[2:3] op_sel:[0,1,0]
	v_pk_fma_f32 v[0:1], v[120:121], v[74:75], v[0:1] op_sel:[0,1,0]
	s_waitcnt vmcnt(9)
	v_pk_fma_f32 v[6:7], v[126:127], v[60:61], v[6:7] op_sel_hi:[1,0,1]
	v_pk_fma_f32 v[4:5], v[124:125], v[60:61], v[4:5] op_sel_hi:[1,0,1]
	v_pk_fma_f32 v[10:11], v[126:127], v[68:69], v[10:11] op_sel_hi:[1,0,1]
	v_pk_fma_f32 v[8:9], v[124:125], v[68:69], v[8:9] op_sel_hi:[1,0,1]
	v_pk_fma_f32 v[2:3], v[126:127], v[76:77], v[2:3] op_sel_hi:[1,0,1]
	v_pk_fma_f32 v[0:1], v[124:125], v[76:77], v[0:1] op_sel_hi:[1,0,1]
	s_waitcnt vmcnt(8)
	v_pk_fma_f32 v[6:7], v[130:131], v[84:85], v[6:7] op_sel_hi:[1,0,1]
	v_pk_fma_f32 v[4:5], v[128:129], v[84:85], v[4:5] op_sel_hi:[1,0,1]
	v_pk_fma_f32 v[10:11], v[130:131], v[86:87], v[10:11] op_sel_hi:[1,0,1]
	v_pk_fma_f32 v[8:9], v[128:129], v[86:87], v[8:9] op_sel_hi:[1,0,1]
	v_pk_fma_f32 v[2:3], v[130:131], v[88:89], v[2:3] op_sel_hi:[1,0,1]
	v_pk_fma_f32 v[0:1], v[128:129], v[88:89], v[0:1] op_sel_hi:[1,0,1]
	s_branch .Lgv_loop
.Lgv_tail:
	v_mov_b32_e32 v74, s13
	ds_read_b128 v[54:57], v74
	ds_read_b128 v[58:61], v74 offset:16
	ds_read_b128 v[62:65], v74 offset:512
	ds_read_b128 v[66:69], v74 offset:528
	ds_read_b128 v[70:73], v74 offset:1024
	ds_read_b128 v[74:77], v74 offset:1040
	s_waitcnt lgkmcnt(5)
	v_mov_b32_e32 v78, v57
	s_waitcnt lgkmcnt(3)
	v_mov_b32_e32 v80, v65
	v_mov_b32_e32 v84, v61
	s_waitcnt lgkmcnt(1)
	v_mov_b32_e32 v82, v73
	v_mov_b32_e32 v86, v69
	s_waitcnt lgkmcnt(0)
	v_mov_b32_e32 v88, v77
	s_add_i32 s13, s13, 32
	s_waitcnt vmcnt(7)
	v_pk_fma_f32 v[6:7], v[102:103], v[54:55], v[6:7] op_sel_hi:[1,0,1]
	v_pk_fma_f32 v[4:5], v[100:101], v[54:55], v[4:5] op_sel_hi:[1,0,1]
	v_pk_fma_f32 v[10:11], v[102:103], v[62:63], v[10:11] op_sel_hi:[1,0,1]
	v_pk_fma_f32 v[8:9], v[100:101], v[62:63], v[8:9] op_sel_hi:[1,0,1]
	v_pk_fma_f32 v[2:3], v[102:103], v[70:71], v[2:3] op_sel_hi:[1,0,1]
	v_pk_fma_f32 v[0:1], v[100:101], v[70:71], v[0:1] op_sel_hi:[1,0,1]
	s_waitcnt vmcnt(6)
	v_pk_fma_f32 v[4:5], v[104:105], v[54:55], v[4:5] op_sel:[0,1,0]
	v_pk_fma_f32 v[6:7], v[106:107], v[54:55], v[6:7] op_sel:[0,1,0]
	v_pk_fma_f32 v[8:9], v[104:105], v[62:63], v[8:9] op_sel:[0,1,0]
	v_pk_fma_f32 v[10:11], v[106:107], v[62:63], v[10:11] op_sel:[0,1,0]
	v_pk_fma_f32 v[0:1], v[104:105], v[70:71], v[0:1] op_sel:[0,1,0]
	v_pk_fma_f32 v[2:3], v[106:107], v[70:71], v[2:3] op_sel:[0,1,0]
	s_waitcnt vmcnt(5)
	v_pk_fma_f32 v[6:7], v[110:111], v[56:57], v[6:7] op_sel_hi:[1,0,1]
	v_pk_fma_f32 v[4:5], v[108:109], v[56:57], v[4:5] op_sel_hi:[1,0,1]
	v_pk_fma_f32 v[10:11], v[110:111], v[64:65], v[10:11] op_sel_hi:[1,0,1]
	v_pk_fma_f32 v[8:9], v[108:109], v[64:65], v[8:9] op_sel_hi:[1,0,1]
	v_pk_fma_f32 v[2:3], v[110:111], v[72:73], v[2:3] op_sel_hi:[1,0,1]
	v_pk_fma_f32 v[0:1], v[108:109], v[72:73], v[0:1] op_sel_hi:[1,0,1]
	s_waitcnt vmcnt(4)
	v_pk_fma_f32 v[6:7], v[114:115], v[78:79], v[6:7] op_sel_hi:[1,0,1]
	v_pk_fma_f32 v[4:5], v[112:113], v[78:79], v[4:5] op_sel_hi:[1,0,1]
	v_pk_fma_f32 v[10:11], v[114:115], v[80:81], v[10:11] op_sel_hi:[1,0,1]
	v_pk_fma_f32 v[8:9], v[112:113], v[80:81], v[8:9] op_sel_hi:[1,0,1]
	v_pk_fma_f32 v[2:3], v[114:115], v[82:83], v[2:3] op_sel_hi:[1,0,1]
	v_pk_fma_f32 v[0:1], v[112:113], v[82:83], v[0:1] op_sel_hi:[1,0,1]
	s_waitcnt vmcnt(3)
	v_pk_fma_f32 v[6:7], v[118:119], v[58:59], v[6:7] op_sel_hi:[1,0,1]
	v_pk_fma_f32 v[4:5], v[116:117], v[58:59], v[4:5] op_sel_hi:[1,0,1]
	v_pk_fma_f32 v[10:11], v[118:119], v[66:67], v[10:11] op_sel_hi:[1,0,1]
	v_pk_fma_f32 v[8:9], v[116:117], v[66:67], v[8:9] op_sel_hi:[1,0,1]
	v_pk_fma_f32 v[2:3], v[118:119], v[74:75], v[2:3] op_sel_hi:[1,0,1]
	v_pk_fma_f32 v[0:1], v[116:117], v[74:75], v[0:1] op_sel_hi:[1,0,1]
	s_waitcnt vmcnt(2)
	v_pk_fma_f32 v[6:7], v[122:123], v[58:59], v[6:7] op_sel:[0,1,0]
	v_pk_fma_f32 v[4:5], v[120:121], v[58:59], v[4:5] op_sel:[0,1,0]
	v_pk_fma_f32 v[10:11], v[122:123], v[66:67], v[10:11] op_sel:[0,1,0]
	v_pk_fma_f32 v[8:9], v[120:121], v[66:67], v[8:9] op_sel:[0,1,0]
	v_pk_fma_f32 v[2:3], v[122:123], v[74:75], v[2:3] op_sel:[0,1,0]
	v_pk_fma_f32 v[0:1], v[120:121], v[74:75], v[0:1] op_sel:[0,1,0]
	s_waitcnt vmcnt(1)
	v_pk_fma_f32 v[6:7], v[126:127], v[60:61], v[6:7] op_sel_hi:[1,0,1]
	v_pk_fma_f32 v[4:5], v[124:125], v[60:61], v[4:5] op_sel_hi:[1,0,1]
	v_pk_fma_f32 v[10:11], v[126:127], v[68:69], v[10:11] op_sel_hi:[1,0,1]
	v_pk_fma_f32 v[8:9], v[124:125], v[68:69], v[8:9] op_sel_hi:[1,0,1]
	v_pk_fma_f32 v[2:3], v[126:127], v[76:77], v[2:3] op_sel_hi:[1,0,1]
	v_pk_fma_f32 v[0:1], v[124:125], v[76:77], v[0:1] op_sel_hi:[1,0,1]
	s_waitcnt vmcnt(0)
	v_pk_fma_f32 v[6:7], v[130:131], v[84:85], v[6:7] op_sel_hi:[1,0,1]
	v_pk_fma_f32 v[4:5], v[128:129], v[84:85], v[4:5] op_sel_hi:[1,0,1]
	v_pk_fma_f32 v[10:11], v[130:131], v[86:87], v[10:11] op_sel_hi:[1,0,1]
	v_pk_fma_f32 v[8:9], v[128:129], v[86:87], v[8:9] op_sel_hi:[1,0,1]
	v_pk_fma_f32 v[2:3], v[130:131], v[88:89], v[2:3] op_sel_hi:[1,0,1]
	v_pk_fma_f32 v[0:1], v[128:129], v[88:89], v[0:1] op_sel_hi:[1,0,1]
	s_lshl_b32 s12, s12, 4
	s_add_i32 s12, s12, s29
	s_mul_i32 s13, s12, 3
	s_mul_i32 s12, s12, 0x24000
	s_mul_hi_i32 s13, s13, 0xc000
	s_add_u32 s12, s19, s12
	s_addc_u32 s13, s20, s13
	v_lshl_add_u64 v[14:15], v[14:15], 2, s[12:13]
	global_store_dwordx4 v[14:15], v[4:7], off
	s_add_i32 s28, s28, s66
	s_cmpk_gt_i32 s28, 0xbf
	v_add_co_u32_e32 v4, vcc, 0xc000, v14
	s_nop 1
	v_addc_co_u32_e32 v5, vcc, 0, v15, vcc
	global_store_dwordx4 v[4:5], v[8:11], off
	v_add_co_u32_e32 v4, vcc, 0x18000, v14
	s_nop 1
	v_addc_co_u32_e32 v5, vcc, 0, v15, vcc
	global_store_dwordx4 v[4:5], v[0:3], off
	s_cbranch_scc0 .LBB0_24
	s_movk_i32 s12, 0x600
